# attention softmax fast path, slow path (max raised) moved out of line: no taken branch in common path
# baseline (speedup 1.0000x reference)
.LBB0_513:
	s_lshl_b32 s4, s76, 14
	s_add_i32 s4, s4, 0
	v_add3_u32 v132, s4, v221, v220
	ds_read_b128 v[128:131], v132
	ds_read_b128 v[132:135], v132 offset:8192
	v_add3_u32 v196, s4, v222, v220
	ds_read_b128 v[192:195], v196
	ds_read_b128 v[196:199], v196 offset:8192
	s_waitcnt lgkmcnt(3)
	v_mfma_f32_32x32x16_bf16 v[144:159], v[128:131], v[160:163], 0
	s_waitcnt lgkmcnt(2)
	v_mfma_f32_32x32x16_bf16 v[128:143], v[132:135], v[160:163], 0
	s_waitcnt lgkmcnt(1)
	v_mfma_f32_32x32x16_bf16 v[144:159], v[192:195], v[164:167], v[144:159]
	s_waitcnt lgkmcnt(0)
	v_mfma_f32_32x32x16_bf16 v[128:143], v[196:199], v[164:167], v[128:143]
	v_add3_u32 v196, s4, v223, v220
	ds_read_b128 v[192:195], v196
	ds_read_b128 v[196:199], v196 offset:8192
	s_waitcnt lgkmcnt(1)
	v_mfma_f32_32x32x16_bf16 v[144:159], v[192:195], v[168:171], v[144:159]
	s_waitcnt lgkmcnt(0)
	v_mfma_f32_32x32x16_bf16 v[128:143], v[196:199], v[168:171], v[128:143]
	v_add3_u32 v196, s4, v224, v220
	ds_read_b128 v[192:195], v196
	ds_read_b128 v[196:199], v196 offset:8192
	s_waitcnt lgkmcnt(1)
	v_mfma_f32_32x32x16_bf16 v[144:159], v[192:195], v[172:175], v[144:159]
	s_waitcnt lgkmcnt(0)
	v_mfma_f32_32x32x16_bf16 v[128:143], v[196:199], v[172:175], v[128:143]
	v_add3_u32 v196, s4, v225, v220
	ds_read_b128 v[192:195], v196
	ds_read_b128 v[196:199], v196 offset:8192
	s_waitcnt lgkmcnt(1)
	v_mfma_f32_32x32x16_bf16 v[144:159], v[192:195], v[176:179], v[144:159]
	s_waitcnt lgkmcnt(0)
	v_mfma_f32_32x32x16_bf16 v[128:143], v[196:199], v[176:179], v[128:143]
	v_add3_u32 v196, s4, v227, v220
	ds_read_b128 v[192:195], v196
	ds_read_b128 v[196:199], v196 offset:8192
	s_waitcnt lgkmcnt(1)
	v_mfma_f32_32x32x16_bf16 v[144:159], v[192:195], v[180:183], v[144:159]
	s_waitcnt lgkmcnt(0)
	v_mfma_f32_32x32x16_bf16 v[128:143], v[196:199], v[180:183], v[128:143]
	v_add3_u32 v196, s4, v228, v220
	ds_read_b128 v[192:195], v196
	ds_read_b128 v[196:199], v196 offset:8192
	s_waitcnt lgkmcnt(1)
	v_mfma_f32_32x32x16_bf16 v[144:159], v[192:195], v[184:187], v[144:159]
	s_waitcnt lgkmcnt(0)
	v_mfma_f32_32x32x16_bf16 v[128:143], v[196:199], v[184:187], v[128:143]
	v_add3_u32 v196, s4, v229, v220
	ds_read_b128 v[192:195], v196
	ds_read_b128 v[196:199], v196 offset:8192
	s_waitcnt lgkmcnt(1)
	v_mfma_f32_32x32x16_bf16 v[144:159], v[192:195], v[188:191], v[144:159]
	s_waitcnt lgkmcnt(0)
	v_mfma_f32_32x32x16_bf16 v[128:143], v[196:199], v[188:191], v[128:143]
	s_nop 9
	v_max_f32_e32 v192, v144, v145
	v_max3_f32 v192, v192, v146, v147
	v_max3_f32 v192, v192, v148, v149
	v_max3_f32 v192, v192, v150, v151
	v_max3_f32 v192, v192, v152, v153
	v_max3_f32 v192, v192, v154, v155
	v_max3_f32 v192, v192, v156, v157
	v_max3_f32 v192, v192, v158, v159
	v_max3_f32 v192, v192, v128, v129
	v_max3_f32 v192, v192, v130, v131
	v_max3_f32 v192, v192, v132, v133
	v_max3_f32 v192, v192, v134, v135
	v_max3_f32 v192, v192, v136, v137
	v_max3_f32 v192, v192, v138, v139
	v_max3_f32 v192, v192, v140, v141
	v_max3_f32 v192, v192, v142, v143
	v_mov_b32_e32 v193, v192
	s_nop 1
	v_permlane32_swap_b32_e32 v192, v193
	v_max_f32_e32 v192, v192, v193
	v_sub_f32_e32 v193, v192, v231
	v_cmp_ge_f32_e32 vcc, s38, v193
	s_cmp_eq_u64 vcc, exec
	s_cbranch_scc0 .Lsmf1_slow
	v_mov_b32_e32 v233, 1.0
.Lsmf1_join:
	v_fmamk_f32 v144, v144, 0x3e0293ee, v236
	v_fmamk_f32 v145, v145, 0x3e0293ee, v236
	v_fmamk_f32 v146, v146, 0x3e0293ee, v236
	v_fmamk_f32 v147, v147, 0x3e0293ee, v236
	v_fmamk_f32 v148, v148, 0x3e0293ee, v236
	v_fmamk_f32 v149, v149, 0x3e0293ee, v236
	v_fmamk_f32 v150, v150, 0x3e0293ee, v236
	v_fmamk_f32 v151, v151, 0x3e0293ee, v236
	v_fmamk_f32 v152, v152, 0x3e0293ee, v236
	v_fmamk_f32 v153, v153, 0x3e0293ee, v236
	v_fmamk_f32 v154, v154, 0x3e0293ee, v236
	v_fmamk_f32 v155, v155, 0x3e0293ee, v236
	v_fmamk_f32 v156, v156, 0x3e0293ee, v236
	v_fmamk_f32 v157, v157, 0x3e0293ee, v236
	v_fmamk_f32 v158, v158, 0x3e0293ee, v236
	v_fmamk_f32 v159, v159, 0x3e0293ee, v236
	v_fmamk_f32 v128, v128, 0x3e0293ee, v236
	v_fmamk_f32 v129, v129, 0x3e0293ee, v236
	v_fmamk_f32 v130, v130, 0x3e0293ee, v236
	v_fmamk_f32 v131, v131, 0x3e0293ee, v236
	v_fmamk_f32 v132, v132, 0x3e0293ee, v236
	v_fmamk_f32 v133, v133, 0x3e0293ee, v236
	v_fmamk_f32 v134, v134, 0x3e0293ee, v236
	v_fmamk_f32 v135, v135, 0x3e0293ee, v236
	v_fmamk_f32 v136, v136, 0x3e0293ee, v236
	v_fmamk_f32 v137, v137, 0x3e0293ee, v236
	v_fmamk_f32 v138, v138, 0x3e0293ee, v236
	v_fmamk_f32 v139, v139, 0x3e0293ee, v236
	v_fmamk_f32 v140, v140, 0x3e0293ee, v236
	v_fmamk_f32 v141, v141, 0x3e0293ee, v236
	v_fmamk_f32 v142, v142, 0x3e0293ee, v236
	v_fmamk_f32 v192, v143, 0x3e0293ee, v236
	v_exp_f32_e32 v143, v144
	v_exp_f32_e32 v145, v145
	v_exp_f32_e32 v146, v146
	v_exp_f32_e32 v147, v147
	v_exp_f32_e32 v148, v148
	v_exp_f32_e32 v193, v128
	v_exp_f32_e32 v149, v149
	v_add_f32_e32 v128, v145, v143
	v_exp_f32_e32 v150, v150
	v_add_f32_e32 v128, v146, v128
	v_exp_f32_e32 v151, v151
	v_add_f32_e32 v128, v147, v128
	v_exp_f32_e32 v152, v152
	v_add_f32_e32 v128, v148, v128
	v_exp_f32_e32 v153, v153
	v_add_f32_e32 v128, v149, v128
	v_exp_f32_e32 v154, v154
	v_add_f32_e32 v128, v150, v128
	v_exp_f32_e32 v155, v155
	v_add_f32_e32 v128, v151, v128
	v_exp_f32_e32 v156, v156
	v_add_f32_e32 v128, v152, v128
	v_exp_f32_e32 v157, v157
	v_add_f32_e32 v128, v153, v128
	v_exp_f32_e32 v158, v158
	v_add_f32_e32 v128, v154, v128
	v_exp_f32_e32 v159, v159
	v_add_f32_e32 v128, v155, v128
	v_add_f32_e32 v128, v156, v128
	v_exp_f32_e32 v194, v129
	v_add_f32_e32 v128, v157, v128
	v_exp_f32_e32 v195, v130
	v_add_f32_e32 v128, v158, v128
	v_exp_f32_e32 v196, v131
	v_add_f32_e32 v128, v159, v128
	v_exp_f32_e32 v197, v132
	v_add_f32_e32 v128, v193, v128
	v_exp_f32_e32 v198, v133
	v_add_f32_e32 v128, v194, v128
	v_exp_f32_e32 v199, v134
	v_add_f32_e32 v128, v195, v128
	v_exp_f32_e32 v135, v135
	v_add_f32_e32 v128, v196, v128
	v_exp_f32_e32 v200, v136
	v_add_f32_e32 v128, v197, v128
	v_exp_f32_e32 v201, v137
	v_add_f32_e32 v128, v198, v128
	v_exp_f32_e32 v202, v138
	v_add_f32_e32 v128, v199, v128
	v_exp_f32_e32 v203, v139
	v_add_f32_e32 v128, v135, v128
	v_exp_f32_e32 v204, v140
	v_add_f32_e32 v128, v200, v128
	v_exp_f32_e32 v205, v141
	v_add_f32_e32 v128, v201, v128
	v_exp_f32_e32 v206, v142
	v_add_f32_e32 v128, v202, v128
	v_exp_f32_e32 v192, v192
	v_add_f32_e32 v128, v203, v128
	v_add_f32_e32 v128, v204, v128
	v_add_f32_e32 v128, v205, v128
	v_add_f32_e32 v128, v206, v128
	v_add_f32_e32 v128, v192, v128
	v_mov_b32_e32 v129, v128
	s_nop 1
	v_permlane32_swap_b32_e32 v128, v129
	v_add_f32_e32 v144, v128, v129
	v_fmac_f32_e32 v144, v232, v233
	v_cvt_pk_bf16_f32 v128, v143, v145
	v_cvt_pk_bf16_f32 v129, v146, v147
	v_cvt_pk_bf16_f32 v130, v148, v149
	v_cvt_pk_bf16_f32 v131, v150, v151
	v_cvt_pk_bf16_f32 v136, v152, v153
	v_cvt_pk_bf16_f32 v137, v154, v155
	v_cvt_pk_bf16_f32 v138, v156, v157
	v_cvt_pk_bf16_f32 v139, v158, v159
	v_cvt_pk_bf16_f32 v132, v193, v194
	v_cvt_pk_bf16_f32 v133, v195, v196
	v_cvt_pk_bf16_f32 v134, v197, v198
	v_cvt_pk_bf16_f32 v135, v199, v135
	v_cvt_pk_bf16_f32 v140, v200, v201
	v_cvt_pk_bf16_f32 v141, v202, v203
	v_cvt_pk_bf16_f32 v142, v204, v205
	v_cvt_pk_bf16_f32 v143, v206, v192
	s_nop 0
	v_permlane32_swap_b32_e32 v128, v130
	v_permlane32_swap_b32_e32 v129, v131
	v_permlane32_swap_b32_e32 v136, v138
	v_permlane32_swap_b32_e32 v137, v139
	v_permlane32_swap_b32_e32 v132, v134
	v_permlane32_swap_b32_e32 v133, v135
	v_permlane32_swap_b32_e32 v140, v142
	v_permlane32_swap_b32_e32 v141, v143
	v_lshl_add_u32 v145, s76, 15, v230
	ds_read_b64_tr_b16 v[146:147], v145 offset:0
	ds_read_b64_tr_b16 v[148:149], v145 offset:0x1000
	ds_read_b64_tr_b16 v[150:151], v145 offset:0x2000
	ds_read_b64_tr_b16 v[152:153], v145 offset:0x3000
	ds_read_b64_tr_b16 v[154:155], v145 offset:0x4000
	ds_read_b64_tr_b16 v[156:157], v145 offset:0x5000
	ds_read_b64_tr_b16 v[192:193], v145 offset:0x6000
	ds_read_b64_tr_b16 v[194:195], v145 offset:0x7000
	ds_read_b64_tr_b16 v[196:197], v145 offset:0x200
	ds_read_b64_tr_b16 v[198:199], v145 offset:0x1200
	ds_read_b64_tr_b16 v[200:201], v145 offset:0x2200
	ds_read_b64_tr_b16 v[202:203], v145 offset:0x3200
	ds_read_b64_tr_b16 v[204:205], v145 offset:0x4200
	ds_read_b64_tr_b16 v[206:207], v145 offset:0x5200
	ds_read_b64_tr_b16 v[232:233], v145 offset:0x6200
	ds_read_b64_tr_b16 v[234:235], v145 offset:0x7200
	s_waitcnt lgkmcnt(8)
	s_nop 0
	v_mfma_f32_32x32x16_bf16 v[0:15], v[128:131], v[146:149], v[0:15]
	v_mfma_f32_32x32x16_bf16 v[0:15], v[136:139], v[150:153], v[0:15]
	v_mfma_f32_32x32x16_bf16 v[0:15], v[132:135], v[154:157], v[0:15]
	v_mfma_f32_32x32x16_bf16 v[0:15], v[140:143], v[192:195], v[0:15]
	ds_read_b64_tr_b16 v[146:147], v145 offset:0x400
	ds_read_b64_tr_b16 v[148:149], v145 offset:0x1400
	ds_read_b64_tr_b16 v[150:151], v145 offset:0x2400
	ds_read_b64_tr_b16 v[152:153], v145 offset:0x3400
	ds_read_b64_tr_b16 v[154:155], v145 offset:0x4400
	ds_read_b64_tr_b16 v[156:157], v145 offset:0x5400
	ds_read_b64_tr_b16 v[192:193], v145 offset:0x6400
	ds_read_b64_tr_b16 v[194:195], v145 offset:0x7400
	s_waitcnt lgkmcnt(8)
	v_mfma_f32_32x32x16_bf16 v[112:127], v[128:131], v[196:199], v[112:127]
	v_mfma_f32_32x32x16_bf16 v[112:127], v[136:139], v[200:203], v[112:127]
	v_mfma_f32_32x32x16_bf16 v[112:127], v[132:135], v[204:207], v[112:127]
	v_mfma_f32_32x32x16_bf16 v[112:127], v[140:143], v[232:235], v[112:127]
	ds_read_b64_tr_b16 v[196:197], v145 offset:0x600
	ds_read_b64_tr_b16 v[198:199], v145 offset:0x1600
	ds_read_b64_tr_b16 v[200:201], v145 offset:0x2600
	ds_read_b64_tr_b16 v[202:203], v145 offset:0x3600
	ds_read_b64_tr_b16 v[204:205], v145 offset:0x4600
	ds_read_b64_tr_b16 v[206:207], v145 offset:0x5600
	ds_read_b64_tr_b16 v[232:233], v145 offset:0x6600
	ds_read_b64_tr_b16 v[234:235], v145 offset:0x7600
	s_waitcnt lgkmcnt(8)
	v_mfma_f32_32x32x16_bf16 v[96:111], v[128:131], v[146:149], v[96:111]
	v_mfma_f32_32x32x16_bf16 v[96:111], v[136:139], v[150:153], v[96:111]
	v_mfma_f32_32x32x16_bf16 v[96:111], v[132:135], v[154:157], v[96:111]
	v_mfma_f32_32x32x16_bf16 v[96:111], v[140:143], v[192:195], v[96:111]
	ds_read_b64_tr_b16 v[146:147], v145 offset:0x800
	ds_read_b64_tr_b16 v[148:149], v145 offset:0x1800
	ds_read_b64_tr_b16 v[150:151], v145 offset:0x2800
	ds_read_b64_tr_b16 v[152:153], v145 offset:0x3800
	ds_read_b64_tr_b16 v[154:155], v145 offset:0x4800
	ds_read_b64_tr_b16 v[156:157], v145 offset:0x5800
	ds_read_b64_tr_b16 v[192:193], v145 offset:0x6800
	ds_read_b64_tr_b16 v[194:195], v145 offset:0x7800
	s_waitcnt lgkmcnt(8)
	v_mfma_f32_32x32x16_bf16 v[80:95], v[128:131], v[196:199], v[80:95]
	v_mfma_f32_32x32x16_bf16 v[80:95], v[136:139], v[200:203], v[80:95]
	v_mfma_f32_32x32x16_bf16 v[80:95], v[132:135], v[204:207], v[80:95]
	v_mfma_f32_32x32x16_bf16 v[80:95], v[140:143], v[232:235], v[80:95]
	ds_read_b64_tr_b16 v[196:197], v145 offset:0xa00
	ds_read_b64_tr_b16 v[198:199], v145 offset:0x1a00
	ds_read_b64_tr_b16 v[200:201], v145 offset:0x2a00
	ds_read_b64_tr_b16 v[202:203], v145 offset:0x3a00
	ds_read_b64_tr_b16 v[204:205], v145 offset:0x4a00
	ds_read_b64_tr_b16 v[206:207], v145 offset:0x5a00
	ds_read_b64_tr_b16 v[232:233], v145 offset:0x6a00
	ds_read_b64_tr_b16 v[234:235], v145 offset:0x7a00
	s_waitcnt lgkmcnt(8)
	v_mfma_f32_32x32x16_bf16 v[64:79], v[128:131], v[146:149], v[64:79]
	v_mfma_f32_32x32x16_bf16 v[64:79], v[136:139], v[150:153], v[64:79]
	v_mfma_f32_32x32x16_bf16 v[64:79], v[132:135], v[154:157], v[64:79]
	v_mfma_f32_32x32x16_bf16 v[64:79], v[140:143], v[192:195], v[64:79]
	ds_read_b64_tr_b16 v[146:147], v145 offset:0xc00
	ds_read_b64_tr_b16 v[148:149], v145 offset:0x1c00
	ds_read_b64_tr_b16 v[150:151], v145 offset:0x2c00
	ds_read_b64_tr_b16 v[152:153], v145 offset:0x3c00
	ds_read_b64_tr_b16 v[154:155], v145 offset:0x4c00
	ds_read_b64_tr_b16 v[156:157], v145 offset:0x5c00
	ds_read_b64_tr_b16 v[192:193], v145 offset:0x6c00
	ds_read_b64_tr_b16 v[194:195], v145 offset:0x7c00
	s_waitcnt lgkmcnt(8)
	v_mfma_f32_32x32x16_bf16 v[48:63], v[128:131], v[196:199], v[48:63]
	v_mfma_f32_32x32x16_bf16 v[48:63], v[136:139], v[200:203], v[48:63]
	v_mfma_f32_32x32x16_bf16 v[48:63], v[132:135], v[204:207], v[48:63]
	v_mfma_f32_32x32x16_bf16 v[48:63], v[140:143], v[232:235], v[48:63]
	ds_read_b64_tr_b16 v[196:197], v145 offset:0xe00
	ds_read_b64_tr_b16 v[198:199], v145 offset:0x1e00
	ds_read_b64_tr_b16 v[200:201], v145 offset:0x2e00
	ds_read_b64_tr_b16 v[202:203], v145 offset:0x3e00
	ds_read_b64_tr_b16 v[204:205], v145 offset:0x4e00
	ds_read_b64_tr_b16 v[206:207], v145 offset:0x5e00
	ds_read_b64_tr_b16 v[232:233], v145 offset:0x6e00
	ds_read_b64_tr_b16 v[234:235], v145 offset:0x7e00
	s_waitcnt lgkmcnt(8)
	v_mfma_f32_32x32x16_bf16 v[32:47], v[128:131], v[146:149], v[32:47]
	v_mfma_f32_32x32x16_bf16 v[32:47], v[136:139], v[150:153], v[32:47]
	v_mfma_f32_32x32x16_bf16 v[32:47], v[132:135], v[154:157], v[32:47]
	v_mfma_f32_32x32x16_bf16 v[32:47], v[140:143], v[192:195], v[32:47]
	s_waitcnt lgkmcnt(0)
	v_mfma_f32_32x32x16_bf16 v[16:31], v[128:131], v[196:199], v[16:31]
	s_add_i32 s4, s76, 1
	s_cmp_lg_u32 s76, 2
	s_cselect_b32 s76, s4, 0
	s_add_i32 s4, s74, 1
	s_cmp_lg_u32 s74, 2
	s_cselect_b32 s74, s4, 0
	s_add_u32 s22, s22, 0x20000
	v_mfma_f32_32x32x16_bf16 v[16:31], v[136:139], v[200:203], v[16:31]
	s_addc_u32 s23, s23, 0
	s_add_i32 s86, s86, 1
	s_cmp_eq_u32 s22, 0x800000
	v_mfma_f32_32x32x16_bf16 v[16:31], v[132:135], v[204:207], v[16:31]
	v_mfma_f32_32x32x16_bf16 v[16:31], v[140:143], v[232:235], v[16:31]
	s_cbranch_scc1 .LBB0_521
	v_mov_b32_e32 v232, v144
	s_cmp_eq_u32 s22, 0x7e0000
	s_mov_b64 s[4:5], -1
	s_cbranch_scc1 .LBB0_510

.LBB0_520:
	s_waitcnt vmcnt(0) lgkmcnt(0)
	s_barrier
	s_cmp_gt_u32 s86, 61
	s_cbranch_scc0 .LBB0_512
	s_branch .LBB0_513
.Lsmf1_slow:
	v_max_f32_e32 v234, v231, v192
	v_sub_f32_e32 v192, v231, v234
	v_mul_f32_e32 v192, 0x3e0293ee, v192
	v_exp_f32_e32 v192, v192
	s_cselect_b64 s[4:5], -1, 0
	v_cndmask_b32_e64 v233, v192, 1.0, s[4:5]
	v_cmp_gt_f32_e32 vcc, 1.0, v233
	s_cbranch_vccz .LBB0_517
	s_and_saveexec_b64 s[24:25], s[0:1]
	ds_write_b32 v226, v233 offset:128
	s_or_b64 exec, exec, s[24:25]
	s_waitcnt lgkmcnt(0)
	v_add_u32_e32 v192, s21, v210
	ds_read_b128 v[204:207], v192 offset:224
	ds_read_b128 v[200:203], v192 offset:192
	ds_read_b128 v[196:199], v192 offset:160
	ds_read_b128 v[192:195], v192 offset:128
	s_waitcnt lgkmcnt(3)
	v_pk_mul_f32 v[12:13], v[12:13], v[204:205]
	s_waitcnt lgkmcnt(2)
	v_pk_mul_f32 v[8:9], v[8:9], v[200:201]
	s_waitcnt lgkmcnt(1)
	v_pk_mul_f32 v[4:5], v[4:5], v[196:197]
	v_pk_mul_f32 v[14:15], v[14:15], v[206:207]
	v_pk_mul_f32 v[10:11], v[10:11], v[202:203]
	v_pk_mul_f32 v[6:7], v[6:7], v[198:199]
	s_waitcnt lgkmcnt(0)
	v_pk_mul_f32 v[2:3], v[2:3], v[194:195]
	v_pk_mul_f32 v[0:1], v[0:1], v[192:193]
	v_pk_mul_f32 v[124:125], v[124:125], v[204:205]
	v_pk_mul_f32 v[120:121], v[120:121], v[200:201]
	v_pk_mul_f32 v[116:117], v[116:117], v[196:197]
	v_pk_mul_f32 v[126:127], v[126:127], v[206:207]
	v_pk_mul_f32 v[122:123], v[122:123], v[202:203]
	v_pk_mul_f32 v[118:119], v[118:119], v[198:199]
	v_pk_mul_f32 v[114:115], v[114:115], v[194:195]
	v_pk_mul_f32 v[112:113], v[112:113], v[192:193]
	v_pk_mul_f32 v[108:109], v[108:109], v[204:205]
	v_pk_mul_f32 v[104:105], v[104:105], v[200:201]
	v_pk_mul_f32 v[100:101], v[100:101], v[196:197]
	v_pk_mul_f32 v[110:111], v[110:111], v[206:207]
	v_pk_mul_f32 v[106:107], v[106:107], v[202:203]
	v_pk_mul_f32 v[102:103], v[102:103], v[198:199]
	v_pk_mul_f32 v[98:99], v[98:99], v[194:195]
	v_pk_mul_f32 v[96:97], v[96:97], v[192:193]
	v_pk_mul_f32 v[92:93], v[92:93], v[204:205]
	v_pk_mul_f32 v[88:89], v[88:89], v[200:201]
	v_pk_mul_f32 v[84:85], v[84:85], v[196:197]
	v_pk_mul_f32 v[94:95], v[94:95], v[206:207]
	v_pk_mul_f32 v[90:91], v[90:91], v[202:203]
	v_pk_mul_f32 v[86:87], v[86:87], v[198:199]
	v_pk_mul_f32 v[82:83], v[82:83], v[194:195]
	v_pk_mul_f32 v[80:81], v[80:81], v[192:193]
	v_pk_mul_f32 v[76:77], v[76:77], v[204:205]
	v_pk_mul_f32 v[72:73], v[72:73], v[200:201]
	v_pk_mul_f32 v[68:69], v[68:69], v[196:197]
	v_pk_mul_f32 v[78:79], v[78:79], v[206:207]
	v_pk_mul_f32 v[74:75], v[74:75], v[202:203]
	v_pk_mul_f32 v[70:71], v[70:71], v[198:199]
	v_pk_mul_f32 v[66:67], v[66:67], v[194:195]
	v_pk_mul_f32 v[64:65], v[64:65], v[192:193]
	v_pk_mul_f32 v[60:61], v[60:61], v[204:205]
	v_pk_mul_f32 v[56:57], v[56:57], v[200:201]
	v_pk_mul_f32 v[52:53], v[52:53], v[196:197]
	v_pk_mul_f32 v[62:63], v[62:63], v[206:207]
	v_pk_mul_f32 v[58:59], v[58:59], v[202:203]
	v_pk_mul_f32 v[54:55], v[54:55], v[198:199]
	v_pk_mul_f32 v[50:51], v[50:51], v[194:195]
	v_pk_mul_f32 v[48:49], v[48:49], v[192:193]
	v_pk_mul_f32 v[44:45], v[44:45], v[204:205]
	v_pk_mul_f32 v[40:41], v[40:41], v[200:201]
	v_pk_mul_f32 v[36:37], v[36:37], v[196:197]
	v_pk_mul_f32 v[46:47], v[46:47], v[206:207]
	v_pk_mul_f32 v[42:43], v[42:43], v[202:203]
	v_pk_mul_f32 v[38:39], v[38:39], v[198:199]
	v_pk_mul_f32 v[34:35], v[34:35], v[194:195]
	v_pk_mul_f32 v[32:33], v[32:33], v[192:193]
	v_pk_mul_f32 v[28:29], v[28:29], v[204:205]
	v_pk_mul_f32 v[24:25], v[24:25], v[200:201]
	v_pk_mul_f32 v[20:21], v[20:21], v[196:197]
	v_pk_mul_f32 v[30:31], v[30:31], v[206:207]
	v_pk_mul_f32 v[26:27], v[26:27], v[202:203]
	v_pk_mul_f32 v[22:23], v[22:23], v[198:199]
	v_pk_mul_f32 v[18:19], v[18:19], v[194:195]
	v_pk_mul_f32 v[16:17], v[16:17], v[192:193]
.LBB0_517:
	v_cndmask_b32_e64 v231, v234, v231, s[4:5]
	v_mul_f32_e32 v236, 0xbe0293ee, v231
	s_branch .Lsmf1_join

.LBB0_906:
	s_lshl_b32 s4, s80, 14
	s_add_i32 s4, s4, 0
	v_add3_u32 v132, s4, v221, v220
	ds_read_b128 v[128:131], v132
	ds_read_b128 v[132:135], v132 offset:8192
	v_add3_u32 v196, s4, v222, v220
	ds_read_b128 v[192:195], v196
	ds_read_b128 v[196:199], v196 offset:8192
	v_add3_u32 v200, s4, v227, v220
	s_waitcnt lgkmcnt(3)
	v_mfma_f32_32x32x16_bf16 v[144:159], v[128:131], v[160:163], 0
	s_waitcnt lgkmcnt(2)
	v_mfma_f32_32x32x16_bf16 v[128:143], v[132:135], v[160:163], 0
	s_waitcnt lgkmcnt(1)
	v_mfma_f32_32x32x16_bf16 v[144:159], v[192:195], v[164:167], v[144:159]
	s_waitcnt lgkmcnt(0)
	v_mfma_f32_32x32x16_bf16 v[128:143], v[196:199], v[164:167], v[128:143]
	v_add3_u32 v196, s4, v223, v220
	ds_read_b128 v[192:195], v196
	ds_read_b128 v[196:199], v196 offset:8192
	s_waitcnt lgkmcnt(1)
	v_mfma_f32_32x32x16_bf16 v[144:159], v[192:195], v[168:171], v[144:159]
	s_waitcnt lgkmcnt(0)
	v_mfma_f32_32x32x16_bf16 v[128:143], v[196:199], v[168:171], v[128:143]
	v_add3_u32 v196, s4, v225, v220
	ds_read_b128 v[192:195], v196
	ds_read_b128 v[196:199], v196 offset:8192
	s_waitcnt lgkmcnt(1)
	v_mfma_f32_32x32x16_bf16 v[144:159], v[192:195], v[172:175], v[144:159]
	s_waitcnt lgkmcnt(0)
	v_mfma_f32_32x32x16_bf16 v[128:143], v[196:199], v[172:175], v[128:143]
	v_add3_u32 v196, s4, v226, v220
	ds_read_b128 v[192:195], v196
	ds_read_b128 v[196:199], v196 offset:8192
	s_waitcnt lgkmcnt(1)
	v_mfma_f32_32x32x16_bf16 v[144:159], v[192:195], v[176:179], v[144:159]
	s_waitcnt lgkmcnt(0)
	v_mfma_f32_32x32x16_bf16 v[128:143], v[196:199], v[176:179], v[128:143]
	ds_read_b128 v[192:195], v200
	ds_read_b128 v[196:199], v200 offset:8192
	v_add3_u32 v200, s4, v228, v220
	s_waitcnt lgkmcnt(1)
	v_mfma_f32_32x32x16_bf16 v[144:159], v[192:195], v[180:183], v[144:159]
	s_waitcnt lgkmcnt(0)
	v_mfma_f32_32x32x16_bf16 v[128:143], v[196:199], v[180:183], v[128:143]
	ds_read_b128 v[192:195], v200
	ds_read_b128 v[196:199], v200 offset:8192
	v_add3_u32 v200, s4, v229, v220
	s_waitcnt lgkmcnt(1)
	v_mfma_f32_32x32x16_bf16 v[144:159], v[192:195], v[184:187], v[144:159]
	ds_read_b128 v[192:195], v200
	ds_read_b128 v[200:203], v200 offset:8192
	s_waitcnt lgkmcnt(1)
	v_mfma_f32_32x32x16_bf16 v[144:159], v[192:195], v[188:191], v[144:159]
	v_max_f32_e32 v194, v231, v231
	v_mfma_f32_32x32x16_bf16 v[128:143], v[196:199], v[184:187], v[128:143]
	s_nop 9
	v_max_f32_e32 v192, v144, v145
	v_max3_f32 v192, v192, v146, v147
	v_max3_f32 v192, v192, v148, v149
	v_max3_f32 v192, v192, v150, v151
	v_max3_f32 v192, v192, v152, v153
	s_waitcnt lgkmcnt(0)
	v_mfma_f32_32x32x16_bf16 v[128:143], v[200:203], v[188:191], v[128:143]
	v_max3_f32 v192, v192, v154, v155
	v_max3_f32 v192, v192, v156, v157
	v_max3_f32 v192, v192, v158, v159
	s_nop 8
	v_max3_f32 v192, v192, v128, v129
	v_max3_f32 v192, v192, v130, v131
	v_max3_f32 v192, v192, v132, v133
	v_max3_f32 v192, v192, v134, v135
	v_max3_f32 v192, v192, v136, v137
	v_max3_f32 v192, v192, v138, v139
	v_max3_f32 v192, v192, v140, v141
	v_max3_f32 v192, v192, v142, v143
	v_mov_b32_e32 v193, v192
	s_nop 1
	v_permlane32_swap_b32_e32 v192, v193
	v_max_f32_e32 v192, v192, v193
	v_max_f32_e32 v234, v194, v192
	v_sub_f32_e32 v193, v192, v231
	v_cmp_ge_f32_e32 vcc, s42, v193
	s_cmp_eq_u64 vcc, exec
	s_cbranch_scc0 .Lsmf0_slow
	v_mov_b32_e32 v233, 1.0
.Lsmf0_join:
	v_fmamk_f32 v144, v144, 0x3e0293ee, v236
	v_fmamk_f32 v145, v145, 0x3e0293ee, v236
	v_fmamk_f32 v146, v146, 0x3e0293ee, v236
	v_fmamk_f32 v147, v147, 0x3e0293ee, v236
	v_fmamk_f32 v148, v148, 0x3e0293ee, v236
	v_fmamk_f32 v149, v149, 0x3e0293ee, v236
	v_fmamk_f32 v150, v150, 0x3e0293ee, v236
	v_fmamk_f32 v151, v151, 0x3e0293ee, v236
	v_fmamk_f32 v152, v152, 0x3e0293ee, v236
	v_fmamk_f32 v153, v153, 0x3e0293ee, v236
	v_fmamk_f32 v154, v154, 0x3e0293ee, v236
	v_fmamk_f32 v155, v155, 0x3e0293ee, v236
	v_fmamk_f32 v156, v156, 0x3e0293ee, v236
	v_fmamk_f32 v157, v157, 0x3e0293ee, v236
	v_fmamk_f32 v158, v158, 0x3e0293ee, v236
	v_fmamk_f32 v159, v159, 0x3e0293ee, v236
	v_fmamk_f32 v128, v128, 0x3e0293ee, v236
	v_fmamk_f32 v129, v129, 0x3e0293ee, v236
	v_fmamk_f32 v130, v130, 0x3e0293ee, v236
	v_fmamk_f32 v131, v131, 0x3e0293ee, v236
	v_fmamk_f32 v132, v132, 0x3e0293ee, v236
	v_fmamk_f32 v133, v133, 0x3e0293ee, v236
	v_fmamk_f32 v134, v134, 0x3e0293ee, v236
	v_fmamk_f32 v135, v135, 0x3e0293ee, v236
	v_fmamk_f32 v136, v136, 0x3e0293ee, v236
	v_fmamk_f32 v137, v137, 0x3e0293ee, v236
	v_fmamk_f32 v138, v138, 0x3e0293ee, v236
	v_fmamk_f32 v139, v139, 0x3e0293ee, v236
	v_fmamk_f32 v140, v140, 0x3e0293ee, v236
	v_fmamk_f32 v141, v141, 0x3e0293ee, v236
	v_fmamk_f32 v142, v142, 0x3e0293ee, v236
	v_fmamk_f32 v192, v143, 0x3e0293ee, v236
	v_exp_f32_e32 v143, v144
	v_exp_f32_e32 v145, v145
	v_exp_f32_e32 v146, v146
	v_exp_f32_e32 v147, v147
	v_exp_f32_e32 v148, v148
	v_exp_f32_e32 v193, v128
	v_exp_f32_e32 v149, v149
	v_add_f32_e32 v128, v145, v143
	v_exp_f32_e32 v150, v150
	v_add_f32_e32 v128, v146, v128
	v_exp_f32_e32 v151, v151
	v_add_f32_e32 v128, v147, v128
	v_exp_f32_e32 v152, v152
	v_add_f32_e32 v128, v148, v128
	v_exp_f32_e32 v153, v153
	v_add_f32_e32 v128, v149, v128
	v_exp_f32_e32 v154, v154
	v_add_f32_e32 v128, v150, v128
	v_exp_f32_e32 v155, v155
	v_add_f32_e32 v128, v151, v128
	v_exp_f32_e32 v156, v156
	v_add_f32_e32 v128, v152, v128
	v_exp_f32_e32 v157, v157
	v_add_f32_e32 v128, v153, v128
	v_exp_f32_e32 v158, v158
	v_add_f32_e32 v128, v154, v128
	v_exp_f32_e32 v159, v159
	v_add_f32_e32 v128, v155, v128
	v_add_f32_e32 v128, v156, v128
	v_exp_f32_e32 v194, v129
	v_add_f32_e32 v128, v157, v128
	v_exp_f32_e32 v195, v130
	v_add_f32_e32 v128, v158, v128
	v_exp_f32_e32 v196, v131
	v_add_f32_e32 v128, v159, v128
	v_exp_f32_e32 v197, v132
	v_add_f32_e32 v128, v193, v128
	v_exp_f32_e32 v198, v133
	v_add_f32_e32 v128, v194, v128
	v_exp_f32_e32 v199, v134
	v_add_f32_e32 v128, v195, v128
	v_exp_f32_e32 v135, v135
	v_add_f32_e32 v128, v196, v128
	v_exp_f32_e32 v200, v136
	v_add_f32_e32 v128, v197, v128
	v_exp_f32_e32 v201, v137
	v_add_f32_e32 v128, v198, v128
	v_exp_f32_e32 v202, v138
	v_add_f32_e32 v128, v199, v128
	v_exp_f32_e32 v203, v139
	v_add_f32_e32 v128, v135, v128
	v_exp_f32_e32 v204, v140
	v_add_f32_e32 v128, v200, v128
	v_exp_f32_e32 v205, v141
	v_add_f32_e32 v128, v201, v128
	v_exp_f32_e32 v206, v142
	v_add_f32_e32 v128, v202, v128
	v_exp_f32_e32 v192, v192
	v_add_f32_e32 v128, v203, v128
	v_add_f32_e32 v128, v204, v128
	v_add_f32_e32 v128, v205, v128
	v_add_f32_e32 v128, v206, v128
	v_add_f32_e32 v128, v192, v128
	v_mov_b32_e32 v129, v128
	s_nop 1
	v_permlane32_swap_b32_e32 v128, v129
	v_add_f32_e32 v144, v128, v129
	v_fmac_f32_e32 v144, v232, v233
	v_cvt_pk_bf16_f32 v128, v143, v145
	v_cvt_pk_bf16_f32 v129, v146, v147
	v_cvt_pk_bf16_f32 v130, v148, v149
	v_cvt_pk_bf16_f32 v131, v150, v151
	v_cvt_pk_bf16_f32 v136, v152, v153
	v_cvt_pk_bf16_f32 v137, v154, v155
	v_cvt_pk_bf16_f32 v138, v156, v157
	v_cvt_pk_bf16_f32 v139, v158, v159
	v_cvt_pk_bf16_f32 v132, v193, v194
	v_cvt_pk_bf16_f32 v133, v195, v196
	v_cvt_pk_bf16_f32 v134, v197, v198
	v_cvt_pk_bf16_f32 v135, v199, v135
	v_cvt_pk_bf16_f32 v140, v200, v201
	v_cvt_pk_bf16_f32 v141, v202, v203
	v_cvt_pk_bf16_f32 v142, v204, v205
	v_cvt_pk_bf16_f32 v143, v206, v192
	s_nop 0
	v_permlane32_swap_b32_e32 v128, v130
	v_permlane32_swap_b32_e32 v129, v131
	v_permlane32_swap_b32_e32 v136, v138
	v_permlane32_swap_b32_e32 v137, v139
	v_permlane32_swap_b32_e32 v132, v134
	v_permlane32_swap_b32_e32 v133, v135
	v_permlane32_swap_b32_e32 v140, v142
	v_permlane32_swap_b32_e32 v141, v143
	v_lshl_add_u32 v145, s80, 15, v230
	ds_read_b64_tr_b16 v[146:147], v145 offset:0
	ds_read_b64_tr_b16 v[148:149], v145 offset:0x1000
	ds_read_b64_tr_b16 v[150:151], v145 offset:0x2000
	ds_read_b64_tr_b16 v[152:153], v145 offset:0x3000
	ds_read_b64_tr_b16 v[154:155], v145 offset:0x4000
	ds_read_b64_tr_b16 v[156:157], v145 offset:0x5000
	ds_read_b64_tr_b16 v[192:193], v145 offset:0x6000
	ds_read_b64_tr_b16 v[194:195], v145 offset:0x7000
	ds_read_b64_tr_b16 v[196:197], v145 offset:0x200
	ds_read_b64_tr_b16 v[198:199], v145 offset:0x1200
	ds_read_b64_tr_b16 v[200:201], v145 offset:0x2200
	ds_read_b64_tr_b16 v[202:203], v145 offset:0x3200
	ds_read_b64_tr_b16 v[204:205], v145 offset:0x4200
	ds_read_b64_tr_b16 v[206:207], v145 offset:0x5200
	ds_read_b64_tr_b16 v[232:233], v145 offset:0x6200
	ds_read_b64_tr_b16 v[234:235], v145 offset:0x7200
	s_waitcnt lgkmcnt(8)
	s_nop 0
	v_mfma_f32_32x32x16_bf16 v[0:15], v[128:131], v[146:149], v[0:15]
	v_mfma_f32_32x32x16_bf16 v[0:15], v[136:139], v[150:153], v[0:15]
	v_mfma_f32_32x32x16_bf16 v[0:15], v[132:135], v[154:157], v[0:15]
	v_mfma_f32_32x32x16_bf16 v[0:15], v[140:143], v[192:195], v[0:15]
	ds_read_b64_tr_b16 v[146:147], v145 offset:0x400
	ds_read_b64_tr_b16 v[148:149], v145 offset:0x1400
	ds_read_b64_tr_b16 v[150:151], v145 offset:0x2400
	ds_read_b64_tr_b16 v[152:153], v145 offset:0x3400
	ds_read_b64_tr_b16 v[154:155], v145 offset:0x4400
	ds_read_b64_tr_b16 v[156:157], v145 offset:0x5400
	ds_read_b64_tr_b16 v[192:193], v145 offset:0x6400
	ds_read_b64_tr_b16 v[194:195], v145 offset:0x7400
	s_waitcnt lgkmcnt(8)
	v_mfma_f32_32x32x16_bf16 v[112:127], v[128:131], v[196:199], v[112:127]
	v_mfma_f32_32x32x16_bf16 v[112:127], v[136:139], v[200:203], v[112:127]
	v_mfma_f32_32x32x16_bf16 v[112:127], v[132:135], v[204:207], v[112:127]
	v_mfma_f32_32x32x16_bf16 v[112:127], v[140:143], v[232:235], v[112:127]
	ds_read_b64_tr_b16 v[196:197], v145 offset:0x600
	ds_read_b64_tr_b16 v[198:199], v145 offset:0x1600
	ds_read_b64_tr_b16 v[200:201], v145 offset:0x2600
	ds_read_b64_tr_b16 v[202:203], v145 offset:0x3600
	ds_read_b64_tr_b16 v[204:205], v145 offset:0x4600
	ds_read_b64_tr_b16 v[206:207], v145 offset:0x5600
	ds_read_b64_tr_b16 v[232:233], v145 offset:0x6600
	ds_read_b64_tr_b16 v[234:235], v145 offset:0x7600
	s_waitcnt lgkmcnt(8)
	v_mfma_f32_32x32x16_bf16 v[96:111], v[128:131], v[146:149], v[96:111]
	v_mfma_f32_32x32x16_bf16 v[96:111], v[136:139], v[150:153], v[96:111]
	v_mfma_f32_32x32x16_bf16 v[96:111], v[132:135], v[154:157], v[96:111]
	v_mfma_f32_32x32x16_bf16 v[96:111], v[140:143], v[192:195], v[96:111]
	ds_read_b64_tr_b16 v[146:147], v145 offset:0x800
	ds_read_b64_tr_b16 v[148:149], v145 offset:0x1800
	ds_read_b64_tr_b16 v[150:151], v145 offset:0x2800
	ds_read_b64_tr_b16 v[152:153], v145 offset:0x3800
	ds_read_b64_tr_b16 v[154:155], v145 offset:0x4800
	ds_read_b64_tr_b16 v[156:157], v145 offset:0x5800
	ds_read_b64_tr_b16 v[192:193], v145 offset:0x6800
	ds_read_b64_tr_b16 v[194:195], v145 offset:0x7800
	s_waitcnt lgkmcnt(8)
	v_mfma_f32_32x32x16_bf16 v[80:95], v[128:131], v[196:199], v[80:95]
	v_mfma_f32_32x32x16_bf16 v[80:95], v[136:139], v[200:203], v[80:95]
	v_mfma_f32_32x32x16_bf16 v[80:95], v[132:135], v[204:207], v[80:95]
	v_mfma_f32_32x32x16_bf16 v[80:95], v[140:143], v[232:235], v[80:95]
	ds_read_b64_tr_b16 v[196:197], v145 offset:0xa00
	ds_read_b64_tr_b16 v[198:199], v145 offset:0x1a00
	ds_read_b64_tr_b16 v[200:201], v145 offset:0x2a00
	ds_read_b64_tr_b16 v[202:203], v145 offset:0x3a00
	ds_read_b64_tr_b16 v[204:205], v145 offset:0x4a00
	ds_read_b64_tr_b16 v[206:207], v145 offset:0x5a00
	ds_read_b64_tr_b16 v[232:233], v145 offset:0x6a00
	ds_read_b64_tr_b16 v[234:235], v145 offset:0x7a00
	s_waitcnt lgkmcnt(8)
	v_mfma_f32_32x32x16_bf16 v[64:79], v[128:131], v[146:149], v[64:79]
	v_mfma_f32_32x32x16_bf16 v[64:79], v[136:139], v[150:153], v[64:79]
	v_mfma_f32_32x32x16_bf16 v[64:79], v[132:135], v[154:157], v[64:79]
	v_mfma_f32_32x32x16_bf16 v[64:79], v[140:143], v[192:195], v[64:79]
	ds_read_b64_tr_b16 v[146:147], v145 offset:0xc00
	ds_read_b64_tr_b16 v[148:149], v145 offset:0x1c00
	ds_read_b64_tr_b16 v[150:151], v145 offset:0x2c00
	ds_read_b64_tr_b16 v[152:153], v145 offset:0x3c00
	ds_read_b64_tr_b16 v[154:155], v145 offset:0x4c00
	ds_read_b64_tr_b16 v[156:157], v145 offset:0x5c00
	ds_read_b64_tr_b16 v[192:193], v145 offset:0x6c00
	ds_read_b64_tr_b16 v[194:195], v145 offset:0x7c00
	s_waitcnt lgkmcnt(8)
	v_mfma_f32_32x32x16_bf16 v[48:63], v[128:131], v[196:199], v[48:63]
	v_mfma_f32_32x32x16_bf16 v[48:63], v[136:139], v[200:203], v[48:63]
	v_mfma_f32_32x32x16_bf16 v[48:63], v[132:135], v[204:207], v[48:63]
	v_mfma_f32_32x32x16_bf16 v[48:63], v[140:143], v[232:235], v[48:63]
	ds_read_b64_tr_b16 v[196:197], v145 offset:0xe00
	ds_read_b64_tr_b16 v[198:199], v145 offset:0x1e00
	ds_read_b64_tr_b16 v[200:201], v145 offset:0x2e00
	ds_read_b64_tr_b16 v[202:203], v145 offset:0x3e00
	ds_read_b64_tr_b16 v[204:205], v145 offset:0x4e00
	ds_read_b64_tr_b16 v[206:207], v145 offset:0x5e00
	ds_read_b64_tr_b16 v[232:233], v145 offset:0x6e00
	ds_read_b64_tr_b16 v[234:235], v145 offset:0x7e00
	s_waitcnt lgkmcnt(8)
	v_mfma_f32_32x32x16_bf16 v[32:47], v[128:131], v[146:149], v[32:47]
	v_mfma_f32_32x32x16_bf16 v[32:47], v[136:139], v[150:153], v[32:47]
	v_mfma_f32_32x32x16_bf16 v[32:47], v[132:135], v[154:157], v[32:47]
	v_mfma_f32_32x32x16_bf16 v[32:47], v[140:143], v[192:195], v[32:47]
	s_waitcnt lgkmcnt(0)
	v_mfma_f32_32x32x16_bf16 v[16:31], v[128:131], v[196:199], v[16:31]
	s_add_i32 s4, s80, 1
	s_cmp_lg_u32 s80, 2
	s_cselect_b32 s80, s4, 0
	s_add_i32 s4, s78, 1
	s_cmp_lg_u32 s78, 2
	s_cselect_b32 s78, s4, 0
	s_add_u32 s22, s22, 0x20000
	v_mfma_f32_32x32x16_bf16 v[16:31], v[136:139], v[200:203], v[16:31]
	s_addc_u32 s23, s23, 0
	s_add_i32 s86, s86, 1
	s_cmp_eq_u32 s22, 0x800000
	v_mfma_f32_32x32x16_bf16 v[16:31], v[132:135], v[204:207], v[16:31]
	v_mfma_f32_32x32x16_bf16 v[16:31], v[140:143], v[232:235], v[16:31]
	s_cbranch_scc1 .LBB0_914
	v_mov_b32_e32 v232, v144
	s_cmp_eq_u32 s22, 0x7e0000
	s_mov_b64 s[4:5], -1
	s_cbranch_scc1 .LBB0_903

.LBB0_913:
	s_waitcnt vmcnt(0) lgkmcnt(0)
	s_barrier
	s_cmp_gt_u32 s86, 61
	s_cbranch_scc0 .LBB0_905
	s_branch .LBB0_906
.Lsmf0_slow:
	v_sub_f32_e32 v192, v231, v234
	v_mul_f32_e32 v192, 0x3e0293ee, v192
	v_exp_f32_e32 v192, v192
	s_cselect_b64 s[4:5], -1, 0
	v_cndmask_b32_e64 v233, v192, 1.0, s[4:5]
	v_cmp_gt_f32_e32 vcc, 1.0, v233
	s_cbranch_vccz .LBB0_910
	s_and_saveexec_b64 s[24:25], s[0:1]
	ds_write_b32 v224, v233 offset:128
	s_or_b64 exec, exec, s[24:25]
	s_waitcnt lgkmcnt(0)
	v_add_u32_e32 v192, s21, v210
	ds_read_b128 v[204:207], v192 offset:224
	ds_read_b128 v[200:203], v192 offset:192
	ds_read_b128 v[196:199], v192 offset:160
	ds_read_b128 v[192:195], v192 offset:128
	s_waitcnt lgkmcnt(3)
	v_pk_mul_f32 v[12:13], v[12:13], v[204:205]
	s_waitcnt lgkmcnt(2)
	v_pk_mul_f32 v[8:9], v[8:9], v[200:201]
	s_waitcnt lgkmcnt(1)
	v_pk_mul_f32 v[4:5], v[4:5], v[196:197]
	v_pk_mul_f32 v[14:15], v[14:15], v[206:207]
	v_pk_mul_f32 v[10:11], v[10:11], v[202:203]
	v_pk_mul_f32 v[6:7], v[6:7], v[198:199]
	s_waitcnt lgkmcnt(0)
	v_pk_mul_f32 v[2:3], v[2:3], v[194:195]
	v_pk_mul_f32 v[0:1], v[0:1], v[192:193]
	v_pk_mul_f32 v[124:125], v[124:125], v[204:205]
	v_pk_mul_f32 v[120:121], v[120:121], v[200:201]
	v_pk_mul_f32 v[116:117], v[116:117], v[196:197]
	v_pk_mul_f32 v[126:127], v[126:127], v[206:207]
	v_pk_mul_f32 v[122:123], v[122:123], v[202:203]
	v_pk_mul_f32 v[118:119], v[118:119], v[198:199]
	v_pk_mul_f32 v[114:115], v[114:115], v[194:195]
	v_pk_mul_f32 v[112:113], v[112:113], v[192:193]
	v_pk_mul_f32 v[108:109], v[108:109], v[204:205]
	v_pk_mul_f32 v[104:105], v[104:105], v[200:201]
	v_pk_mul_f32 v[100:101], v[100:101], v[196:197]
	v_pk_mul_f32 v[110:111], v[110:111], v[206:207]
	v_pk_mul_f32 v[106:107], v[106:107], v[202:203]
	v_pk_mul_f32 v[102:103], v[102:103], v[198:199]
	v_pk_mul_f32 v[98:99], v[98:99], v[194:195]
	v_pk_mul_f32 v[96:97], v[96:97], v[192:193]
	v_pk_mul_f32 v[92:93], v[92:93], v[204:205]
	v_pk_mul_f32 v[88:89], v[88:89], v[200:201]
	v_pk_mul_f32 v[84:85], v[84:85], v[196:197]
	v_pk_mul_f32 v[94:95], v[94:95], v[206:207]
	v_pk_mul_f32 v[90:91], v[90:91], v[202:203]
	v_pk_mul_f32 v[86:87], v[86:87], v[198:199]
	v_pk_mul_f32 v[82:83], v[82:83], v[194:195]
	v_pk_mul_f32 v[80:81], v[80:81], v[192:193]
	v_pk_mul_f32 v[76:77], v[76:77], v[204:205]
	v_pk_mul_f32 v[72:73], v[72:73], v[200:201]
	v_pk_mul_f32 v[68:69], v[68:69], v[196:197]
	v_pk_mul_f32 v[78:79], v[78:79], v[206:207]
	v_pk_mul_f32 v[74:75], v[74:75], v[202:203]
	v_pk_mul_f32 v[70:71], v[70:71], v[198:199]
	v_pk_mul_f32 v[66:67], v[66:67], v[194:195]
	v_pk_mul_f32 v[64:65], v[64:65], v[192:193]
	v_pk_mul_f32 v[60:61], v[60:61], v[204:205]
	v_pk_mul_f32 v[56:57], v[56:57], v[200:201]
	v_pk_mul_f32 v[52:53], v[52:53], v[196:197]
	v_pk_mul_f32 v[62:63], v[62:63], v[206:207]
	v_pk_mul_f32 v[58:59], v[58:59], v[202:203]
	v_pk_mul_f32 v[54:55], v[54:55], v[198:199]
	v_pk_mul_f32 v[50:51], v[50:51], v[194:195]
	v_pk_mul_f32 v[48:49], v[48:49], v[192:193]
	v_pk_mul_f32 v[44:45], v[44:45], v[204:205]
	v_pk_mul_f32 v[40:41], v[40:41], v[200:201]
	v_pk_mul_f32 v[36:37], v[36:37], v[196:197]
	v_pk_mul_f32 v[46:47], v[46:47], v[206:207]
	v_pk_mul_f32 v[42:43], v[42:43], v[202:203]
	v_pk_mul_f32 v[38:39], v[38:39], v[198:199]
	v_pk_mul_f32 v[34:35], v[34:35], v[194:195]
	v_pk_mul_f32 v[32:33], v[32:33], v[192:193]
	v_pk_mul_f32 v[28:29], v[28:29], v[204:205]
	v_pk_mul_f32 v[24:25], v[24:25], v[200:201]
	v_pk_mul_f32 v[20:21], v[20:21], v[196:197]
	v_pk_mul_f32 v[30:31], v[30:31], v[206:207]
	v_pk_mul_f32 v[26:27], v[26:27], v[202:203]
	v_pk_mul_f32 v[22:23], v[22:23], v[198:199]
	v_pk_mul_f32 v[18:19], v[18:19], v[194:195]
	v_pk_mul_f32 v[16:17], v[16:17], v[192:193]
